# ping-pong: mask-word load first in LOAD, only the two LDS-DMA late; COMPUTE waits vmcnt(2) (previous pair's DMA + this mask)
# baseline (speedup 1.0000x reference)
.Lpp_hb:
	s_waitcnt lgkmcnt(0)
	s_barrier
	s_mov_b32 s36, s6
	s_add_i32 s6, s15, -1
	s_cmp_lt_u32 s35, 63
	s_cselect_b32 s10, s6, 63
	s_lshl_b64 s[6:7], s[10:11], 15
	v_lshl_add_u64 v[230:231], v[136:137], 0, s[6:7]
	global_load_dwordx2 v[138:139], v[230:231], off
	s_cmp_gt_u32 s35, s28
	s_cbranch_scc1 .Lpp_skip
	v_add_u32_e32 v149, s5, v140
	v_add_u32_e32 v150, s5, v141
	v_add_u32_sdwa v230, v4, s25 dst_sel:DWORD dst_unused:UNUSED_PAD src0_sel:BYTE_0 src1_sel:DWORD
	v_add_u32_sdwa v231, v4, s25 dst_sel:DWORD dst_unused:UNUSED_PAD src0_sel:BYTE_1 src1_sel:DWORD
	v_add_u32_sdwa v232, v4, s25 dst_sel:DWORD dst_unused:UNUSED_PAD src0_sel:BYTE_2 src1_sel:DWORD
	v_add_u32_sdwa v233, v4, s25 dst_sel:DWORD dst_unused:UNUSED_PAD src0_sel:BYTE_3 src1_sel:DWORD
	v_add_u32_sdwa v234, v3, s25 dst_sel:DWORD dst_unused:UNUSED_PAD src0_sel:BYTE_0 src1_sel:DWORD
	v_add_u32_sdwa v235, v3, s25 dst_sel:DWORD dst_unused:UNUSED_PAD src0_sel:BYTE_1 src1_sel:DWORD
	v_add_u32_sdwa v236, v3, s25 dst_sel:DWORD dst_unused:UNUSED_PAD src0_sel:BYTE_2 src1_sel:DWORD
	v_add_u32_sdwa v237, v3, s25 dst_sel:DWORD dst_unused:UNUSED_PAD src0_sel:BYTE_3 src1_sel:DWORD
	ds_read_b128 v[66:69], v230
	ds_read_b128 v[70:73], v231
	ds_read_b128 v[74:77], v232
	ds_read_b128 v[78:81], v233
	ds_read_b128 v[182:185], v149
	ds_read_b128 v[186:189], v149 offset:2048
	ds_read_b128 v[190:193], v149 offset:4096
	ds_read_b128 v[194:197], v149 offset:6144
	ds_read_b128 v[82:85], v234
	ds_read_b128 v[86:89], v235
	ds_read_b128 v[90:93], v236
	ds_read_b128 v[94:97], v237
	s_waitcnt lgkmcnt(8)
	ds_read_b128 v[198:201], v149 offset:512
	ds_read_b128 v[202:205], v149 offset:2560
	ds_read_b128 v[206:209], v149 offset:4608
	ds_read_b128 v[210:213], v149 offset:6656
	s_waitcnt lgkmcnt(8)
	ds_read_b64_tr_b16 v[152:153], v150
	ds_read_b64_tr_b16 v[154:155], v150 offset:512
	ds_read_b64_tr_b16 v[156:157], v150 offset:1024
	ds_read_b64_tr_b16 v[158:159], v150 offset:1536
	s_waitcnt lgkmcnt(8)
	ds_read_b64_tr_b16 v[160:161], v150 offset:2048
	ds_read_b64_tr_b16 v[162:163], v150 offset:2560
	ds_read_b64_tr_b16 v[164:165], v150 offset:3072
	ds_read_b64_tr_b16 v[166:167], v150 offset:3584
	s_waitcnt lgkmcnt(8)
	ds_read_b64_tr_b16 v[168:169], v150 offset:4096
	ds_read_b64_tr_b16 v[170:171], v150 offset:4608
	ds_read_b64_tr_b16 v[172:173], v150 offset:5120
	ds_read_b64_tr_b16 v[174:175], v150 offset:5632
	s_waitcnt lgkmcnt(8)
	ds_read_b64_tr_b16 v[214:215], v150 offset:6144
	ds_read_b64_tr_b16 v[216:217], v150 offset:6656
	ds_read_b64_tr_b16 v[218:219], v150 offset:7168
	ds_read_b64_tr_b16 v[220:221], v150 offset:7680
	s_add_i32 s7, s36, 0x6000
	s_mov_b32 m0, s36
	global_load_lds_dwordx4 v[6:7], off
	s_mov_b32 m0, s7
	global_load_lds_dwordx4 v[8:9], off
	s_waitcnt lgkmcnt(0)
	s_barrier
	v_mfma_f32_32x32x16_bf16 v[66:81], v[182:185], v[110:113], v[66:81]
	v_mfma_f32_32x32x16_bf16 v[66:81], v[186:189], v[98:101], v[66:81]
	v_mfma_f32_32x32x16_bf16 v[66:81], v[190:193], v[102:105], v[66:81]
	v_mfma_f32_32x32x16_bf16 v[66:81], v[194:197], v[106:109], v[66:81]
	s_cmp_lt_u32 s33, s14
	s_cbranch_scc0 .Lpp_bias
	v_mfma_f32_32x32x16_bf16 v[82:97], v[198:201], v[110:113], v[82:97]
	s_add_i32 s5, s34, 1
	s_cmp_lg_u32 s34, 2
	s_cselect_b32 s34, s5, 0
	v_mfma_f32_32x32x16_bf16 v[82:97], v[202:205], v[98:101], v[82:97]
	s_addk_i32 s31, 0xff00
	s_add_i32 s15, s15, 1
	s_add_i32 s5, s30, s31
	v_mfma_f32_32x32x16_bf16 v[82:97], v[206:209], v[102:105], v[82:97]
	s_add_i32 s33, s33, 64
	s_cmp_eq_u32 s5, 0
	s_cselect_b32 s37, 1, 0
	v_exp_f32_e32 v66, v66
	v_exp_f32_e32 v67, v67
	v_exp_f32_e32 v68, v68
	v_mfma_f32_32x32x16_bf16 v[82:97], v[210:213], v[106:109], v[82:97]
	v_exp_f32_e32 v69, v69
	v_exp_f32_e32 v70, v70
	v_exp_f32_e32 v71, v71
	v_exp_f32_e32 v72, v72
	v_exp_f32_e32 v73, v73
	v_cvt_pk_bf16_f32 v4, v66, v67
	v_cvt_pk_bf16_f32 v5, v68, v69
	v_cvt_pk_bf16_f32 v6, v70, v71
	v_cvt_pk_bf16_f32 v7, v72, v73
	v_exp_f32_e32 v74, v74
	v_exp_f32_e32 v75, v75
	v_mfma_f32_32x32x16_bf16 v[34:49], v[4:7], v[152:155], v[34:49]
	v_exp_f32_e32 v76, v76
	v_exp_f32_e32 v77, v77
	v_exp_f32_e32 v78, v78
	v_mfma_f32_32x32x16_bf16 v[18:33], v[4:7], v[168:171], v[18:33]
	v_exp_f32_e32 v79, v79
	v_exp_f32_e32 v80, v80
	v_exp_f32_e32 v81, v81
	v_mfma_f32_32x32x16_bf16 v[50:65], v[4:7], v[226:229], v[50:65]
	v_cvt_pk_bf16_f32 v8, v74, v75
	v_cvt_pk_bf16_f32 v9, v76, v77
	v_cvt_pk_bf16_f32 v10, v78, v79
	v_cvt_pk_bf16_f32 v11, v80, v81
	v_exp_f32_e32 v82, v82
	v_exp_f32_e32 v83, v83
	v_mfma_f32_32x32x16_bf16 v[34:49], v[8:11], v[156:159], v[34:49]
	v_exp_f32_e32 v84, v84
	v_exp_f32_e32 v85, v85
	v_exp_f32_e32 v86, v86
	v_mfma_f32_32x32x16_bf16 v[18:33], v[8:11], v[172:175], v[18:33]
	v_exp_f32_e32 v87, v87
	v_exp_f32_e32 v88, v88
	v_exp_f32_e32 v89, v89
	v_mfma_f32_32x32x16_bf16 v[50:65], v[8:11], v[226:229], v[50:65]
	v_cvt_pk_bf16_f32 v12, v82, v83
	v_cvt_pk_bf16_f32 v13, v84, v85
	v_cvt_pk_bf16_f32 v14, v86, v87
	v_cvt_pk_bf16_f32 v15, v88, v89
	v_exp_f32_e32 v90, v90
	v_exp_f32_e32 v91, v91
	v_mfma_f32_32x32x16_bf16 v[34:49], v[12:15], v[160:163], v[34:49]
	v_exp_f32_e32 v92, v92
	v_exp_f32_e32 v93, v93
	v_exp_f32_e32 v94, v94
	s_add_i32 s35, s15, -2
	s_lshl_b32 s5, s34, 13
	s_cmp_lt_u32 s15, s27
	s_cselect_b32 s10, s15, s29
	v_mfma_f32_32x32x16_bf16 v[18:33], v[12:15], v[214:217], v[18:33]
	v_exp_f32_e32 v95, v95
	v_exp_f32_e32 v96, v96
	v_exp_f32_e32 v97, v97
	s_lshl_b64 s[6:7], s[10:11], 16
	s_waitcnt vmcnt(2)
	v_mfma_f32_32x32x16_bf16 v[50:65], v[12:15], v[226:229], v[50:65]
	v_cvt_pk_bf16_f32 v222, v90, v91
	v_cvt_pk_bf16_f32 v223, v92, v93
	v_cvt_pk_bf16_f32 v224, v94, v95
	v_cvt_pk_bf16_f32 v225, v96, v97
	v_lshl_add_u64 v[6:7], v[116:117], 0, s[6:7]
	v_lshl_add_u64 v[8:9], v[118:119], 0, s[6:7]
	v_mfma_f32_32x32x16_bf16 v[34:49], v[222:225], v[164:167], v[34:49]
	v_lshrrev_b32_e32 v3, v1, v138
	s_add_i32 s6, s5, 0xffffe000
	v_lshlrev_b32_e32 v3, 4, v3
	s_cmp_lg_u32 s34, 0
	v_and_b32_e32 v4, 0xf0f0f0f0, v3
	v_mfma_f32_32x32x16_bf16 v[18:33], v[222:225], v[218:221], v[18:33]
	v_lshrrev_b32_e32 v3, v1, v139
	s_cselect_b32 s6, s6, 0x4000
	v_lshlrev_b32_e32 v3, 4, v3
	s_add_i32 s6, s20, s6
	v_and_b32_e32 v3, 0xf0f0f0f0, v3
	v_mfma_f32_32x32x16_bf16 v[50:65], v[222:225], v[226:229], v[50:65]
	s_cmp_lg_u32 s37, 0
	s_cbranch_scc1 .LBB0_946
	s_branch .Lpp_hb

.Lpp_skip:
	s_add_i32 s7, s36, 0x6000
	s_mov_b32 m0, s36
	global_load_lds_dwordx4 v[6:7], off
	s_mov_b32 m0, s7
	global_load_lds_dwordx4 v[8:9], off
	s_waitcnt lgkmcnt(0)
	s_barrier
	s_branch .LBB0_954
